# norm loops: no vmcnt drain of the previous rows' stores before the next row loads
# speedup vs baseline: 1.0051x; 1.0051x over previous
; DI void phase_norm(const Params& p, int l, const float* g, int shift_idx, bool skip_ctx, bool from_input) {
;     ...
;   for (int row0 = blockIdx.x * 8 + w; row0 < TT; row0 += 2 * stride) {
;     f32x4 v[2][4];
;     bool act[2];
;     int rows[2];
; #pragma unroll
;     for (int u = 0; u < 2; ++u) {
;       const int row = row0 + u * stride;
;       rows[u] = row;
;       const int b = row / TPB, t = row - b * TPB;
;       act[u] = (row < TT) && !(skip_ctx && t < CTXL);
;       if (act[u]) {
;         const float* xr = xrow_src(p, row, from_input);
; #pragma unroll
;         for (int i = 0; i < 4; ++i) v[u][i] = *(const f32x4*)(xr + lane * 4 + i * 256);
.LBB0_168:
	s_mov_b32 s18, 0x38e38e39
	v_mul_hi_i32 v2, v34, s18
	v_lshrrev_b32_e32 v3, 31, v2
	v_ashrrev_i32_e32 v2, 9, v2
	v_add_u32_e32 v35, v2, v3
	s_movk_i32 s18, 0xf700
	v_mad_i32_i24 v3, v35, s18, v34
	s_movk_i32 s18, 0x100
	v_cmp_gt_i32_e64 s[40:41], s18, v3
	s_movk_i32 s18, 0xff
	v_cmp_lt_i32_e64 s[42:43], s18, v3
	s_mov_b64 s[46:47], -1
	s_and_b64 vcc, exec, s[0:1]
	s_cbranch_vccz .LBB0_174
	s_and_saveexec_b64 s[18:19], s[42:43]
	s_xor_b64 s[46:47], exec, s[18:19]
	v_mul_i32_i24_e32 v2, 0xfffff700, v35
	v_lshl_add_u32 v2, v35, 11, v2
	s_movk_i32 s18, 0xff00
	v_add3_u32 v2, v34, v2, s18
	s_or_saveexec_b64 s[46:47], s[46:47]
	v_readlane_b32 s64, v249, 20
	v_readlane_b32 s78, v249, 34
	v_readlane_b32 s79, v249, 35
	v_readlane_b32 s65, v249, 21
	v_readlane_b32 s66, v249, 22
	v_mov_b64_e32 v[4:5], s[78:79]
	v_readlane_b32 s67, v249, 23
	v_readlane_b32 s68, v249, 24
	v_readlane_b32 s69, v249, 25
	v_readlane_b32 s70, v249, 26
	v_readlane_b32 s71, v249, 27
	v_readlane_b32 s72, v249, 28
	v_readlane_b32 s73, v249, 29
	v_readlane_b32 s74, v249, 30
	v_readlane_b32 s75, v249, 31
	v_readlane_b32 s76, v249, 32
	v_readlane_b32 s77, v249, 33
	s_xor_b64 exec, exec, s[46:47]
	v_lshl_add_u32 v2, v35, 8, v3
	v_mov_b64_e32 v[4:5], s[88:89]
	s_or_b64 exec, exec, s[46:47]
	s_mov_b64 s[46:47], 0

; DI void phase_norm(const Params& p, int l, const float* g, int shift_idx, bool skip_ctx, bool from_input) {
;     ...
;   for (int row0 = blockIdx.x * 8 + w; row0 < TT; row0 += 2 * stride) {
;     f32x4 v[2][4];
;     bool act[2];
;     int rows[2];
; #pragma unroll
;     for (int u = 0; u < 2; ++u) {
;       const int row = row0 + u * stride;
;       rows[u] = row;
;       const int b = row / TPB, t = row - b * TPB;
;       act[u] = (row < TT) && !(skip_ctx && t < CTXL);
;       if (act[u]) {
;         const float* xr = xrow_src(p, row, from_input);
; #pragma unroll
;         for (int i = 0; i < 4; ++i) v[u][i] = *(const f32x4*)(xr + lane * 4 + i * 256);
;       } else {
; #pragma unroll
;         for (int i = 0; i < 4; ++i) v[u][i] = (f32x4){0.f, 0.f, 0.f, 0.f};
;       }
;     }
.LBB0_1471:
	s_mov_b32 s18, 0x38e38e39
	v_mul_hi_i32 v0, v38, s18
	v_lshrrev_b32_e32 v2, 31, v0
	v_ashrrev_i32_e32 v0, 9, v0
	v_add_u32_e32 v34, v0, v2
	v_mul_i32_i24_e32 v0, 0x900, v34
	v_sub_u32_e32 v0, v38, v0
	s_movk_i32 s18, 0x100
	v_cmp_gt_i32_e32 vcc, s18, v0
	v_readlane_b32 s18, v248, 12
	v_readlane_b32 s19, v248, 13
	s_and_b64 s[18:19], s[18:19], vcc
	s_xor_b64 s[44:45], s[18:19], -1
	s_movk_i32 s18, 0xf700
	v_mov_b32_e32 v33, 0
	v_mad_i32_i24 v35, v34, s18, v38
	v_mov_b32_e32 v32, 0
	v_mov_b32_e32 v31, 0
	v_mov_b32_e32 v30, 0
	v_mov_b32_e32 v29, 0
	v_mov_b32_e32 v28, 0
	v_mov_b32_e32 v27, 0
	v_mov_b32_e32 v26, 0
	v_mov_b32_e32 v25, 0
	v_mov_b32_e32 v24, 0
	v_mov_b32_e32 v23, 0
	v_mov_b32_e32 v22, 0
	v_mov_b32_e32 v21, 0
	v_mov_b32_e32 v20, 0
	v_mov_b32_e32 v19, 0
	v_mov_b32_e32 v18, 0
	s_and_saveexec_b64 s[40:41], s[44:45]
	s_cbranch_execz .LBB0_1477
	s_movk_i32 s18, 0xff
	v_cmp_lt_i32_e32 vcc, s18, v35
	s_and_saveexec_b64 s[18:19], vcc
	s_xor_b64 s[42:43], exec, s[18:19]
	v_mul_i32_i24_e32 v0, 0xfffff700, v34
	v_lshl_add_u32 v0, v34, 11, v0
	s_movk_i32 s18, 0xff00
	v_add3_u32 v2, v38, v0, s18
	s_or_saveexec_b64 s[42:43], s[42:43]
	v_readlane_b32 s64, v249, 20
	v_readlane_b32 s78, v249, 34
	v_readlane_b32 s79, v249, 35
	v_readlane_b32 s65, v249, 21
	v_readlane_b32 s66, v249, 22
	v_mov_b64_e32 v[4:5], s[78:79]
	v_readlane_b32 s67, v249, 23
	v_readlane_b32 s68, v249, 24
	v_readlane_b32 s69, v249, 25
	v_readlane_b32 s70, v249, 26
	v_readlane_b32 s71, v249, 27
	v_readlane_b32 s72, v249, 28
	v_readlane_b32 s73, v249, 29
	v_readlane_b32 s74, v249, 30
	v_readlane_b32 s75, v249, 31
	v_readlane_b32 s76, v249, 32
	v_readlane_b32 s77, v249, 33
	s_xor_b64 exec, exec, s[42:43]
	v_lshl_add_u32 v2, v34, 8, v35
	v_mov_b64_e32 v[4:5], s[88:89]
	s_or_b64 exec, exec, s[42:43]
	v_ashrrev_i32_e32 v3, 31, v2
	v_lshlrev_b64 v[2:3], 12, v[2:3]
	v_lshl_add_u64 v[2:3], v[4:5], 0, v[2:3]
	v_lshlrev_b32_e32 v0, 2, v40
	v_lshl_add_u64 v[2:3], v[2:3], 0, v[0:1]
	global_load_dwordx4 v[30:33], v[2:3], off
	global_load_dwordx4 v[26:29], v[2:3], off offset:1024
	global_load_dwordx4 v[22:25], v[2:3], off offset:2048
	global_load_dwordx4 v[18:21], v[2:3], off offset:3072
